# v16 + tap_table loop: h3 loads run one 16-k iteration ahead (issued mid/end of previous iteration), last iteration peeled
# speedup vs baseline: 1.0090x; 1.0022x over previous
.LBB0_542:
	v_and_b32_e32 v255, 7, v0
	v_lshrrev_b32_e32 v254, 3, v0
	v_bfe_u32 v253, v255, 2, 1
	v_lshlrev_b32_e32 v254, 13, v254
	v_lshlrev_b32_e32 v253, 1, v253
	v_and_b32_e32 v250, 1, v255
	v_add_u32_e32 v253, 1, v253
	v_bfe_u32 v255, v255, 1, 1
	v_sub_u32_e32 v253, v253, v250
	v_lshl_add_u32 v254, v253, 11, v254
	v_lshl_add_u32 v254, v255, 10, v254
	global_load_dword v250, v254, s[16:17]
	v_lshlrev_b32_e32 v255, 2, v0
	v_mov_b32_e32 v253, 0
	s_waitcnt vmcnt(0)
	ds_write_b32 v255, v250
	s_waitcnt lgkmcnt(0)
	s_barrier
	s_mov_b64 s[4:5], 0
	v_mov_b32_e32 v12, 0
	v_mov_b32_e32 v13, v5
	v_mov_b32_e32 v24, 0
	v_mov_b32_e32 v25, v5
	v_mov_b32_e32 v14, 0
	v_mov_b32_e32 v15, v5
	v_mov_b32_e32 v28, 0
	v_mov_b32_e32 v29, v5
	v_mov_b32_e32 v16, 0
	v_mov_b32_e32 v17, v5
	v_mov_b32_e32 v30, 0
	v_mov_b32_e32 v31, v5
	v_mov_b32_e32 v18, 0
	v_mov_b32_e32 v19, v5
	v_mov_b32_e32 v38, 0
	v_mov_b32_e32 v39, v5
	v_mov_b32_e32 v40, 0
	v_mov_b32_e32 v41, v5
	v_mov_b32_e32 v20, 0
	v_mov_b32_e32 v21, v5
	v_mov_b32_e32 v44, 0
	v_mov_b32_e32 v45, v5
	v_mov_b32_e32 v22, 0
	v_mov_b32_e32 v23, v5
	v_mov_b32_e32 v46, 0
	v_mov_b32_e32 v47, v5
	v_mov_b32_e32 v26, 0
	v_mov_b32_e32 v27, v5
	v_mov_b32_e32 v48, 0
	v_mov_b32_e32 v49, v5
	v_mov_b32_e32 v50, 0
	v_mov_b32_e32 v51, v5
	v_lshl_add_u64 v[158:159], v[10:11], 0, s[4:5]
	s_mov_b32 s99, 0
	s_mov_b32 s98, 0x181000
	v_lshl_add_u64 v[200:201], v[158:159], 0, s[98:99]
	global_load_dword v32, v[200:201], off offset:-4096
	global_load_dword v33, v[200:201], off offset:-2048
	global_load_dword v42, v[200:201], off
	global_load_dword v43, v[200:201], off offset:2048
	s_mov_b32 s98, 0x183000
	v_lshl_add_u64 v[200:201], v[158:159], 0, s[98:99]
	global_load_dword v52, v[200:201], off offset:-4096
	global_load_dword v53, v[200:201], off offset:-2048
	global_load_dword v54, v[200:201], off
	global_load_dword v55, v[200:201], off offset:2048
	s_mov_b32 s98, 0x185000
	v_lshl_add_u64 v[200:201], v[158:159], 0, s[98:99]
	global_load_dword v58, v[200:201], off offset:-4096
	global_load_dword v59, v[200:201], off offset:-2048
	global_load_dword v62, v[200:201], off
	global_load_dword v63, v[200:201], off offset:2048
	s_mov_b32 s98, 0x187000
	v_lshl_add_u64 v[200:201], v[158:159], 0, s[98:99]
	global_load_dword v64, v[200:201], off offset:-4096
	global_load_dword v65, v[200:201], off offset:-2048
	global_load_dword v68, v[200:201], off
	global_load_dword v69, v[200:201], off offset:2048
	s_mov_b32 s98, 0x189000
	v_lshl_add_u64 v[200:201], v[158:159], 0, s[98:99]
	global_load_dword v70, v[200:201], off offset:-4096
	global_load_dword v71, v[200:201], off offset:-2048
	global_load_dword v72, v[200:201], off
	global_load_dword v73, v[200:201], off offset:2048
	s_mov_b32 s98, 0x18b000
	v_lshl_add_u64 v[200:201], v[158:159], 0, s[98:99]
	global_load_dword v74, v[200:201], off offset:-4096
	global_load_dword v75, v[200:201], off offset:-2048
	global_load_dword v84, v[200:201], off
	global_load_dword v85, v[200:201], off offset:2048
	s_mov_b32 s98, 0x18d000
	v_lshl_add_u64 v[200:201], v[158:159], 0, s[98:99]
	global_load_dword v94, v[200:201], off offset:-4096
	global_load_dword v95, v[200:201], off offset:-2048
	global_load_dword v104, v[200:201], off
	global_load_dword v105, v[200:201], off offset:2048
	s_mov_b32 s98, 0x18f000
	v_lshl_add_u64 v[200:201], v[158:159], 0, s[98:99]
	global_load_dword v112, v[200:201], off offset:-4096
	global_load_dword v113, v[200:201], off offset:-2048
	global_load_dword v116, v[200:201], off
	global_load_dword v117, v[200:201], off offset:2048
	s_mov_b32 s98, 0x191000
	v_lshl_add_u64 v[200:201], v[158:159], 0, s[98:99]
	global_load_dword v122, v[200:201], off offset:-4096
	global_load_dword v123, v[200:201], off offset:-2048
	global_load_dword v126, v[200:201], off
	global_load_dword v127, v[200:201], off offset:2048
	s_mov_b32 s98, 0x193000
	v_lshl_add_u64 v[200:201], v[158:159], 0, s[98:99]
	global_load_dword v130, v[200:201], off offset:-4096
	global_load_dword v131, v[200:201], off offset:-2048
	global_load_dword v138, v[200:201], off
	global_load_dword v139, v[200:201], off offset:2048
	s_mov_b32 s98, 0x195000
	v_lshl_add_u64 v[200:201], v[158:159], 0, s[98:99]
	global_load_dword v140, v[200:201], off offset:-4096
	global_load_dword v141, v[200:201], off offset:-2048
	global_load_dword v144, v[200:201], off
	global_load_dword v145, v[200:201], off offset:2048
	s_mov_b32 s98, 0x197000
	v_lshl_add_u64 v[200:201], v[158:159], 0, s[98:99]
	global_load_dword v150, v[200:201], off offset:-4096
	global_load_dword v151, v[200:201], off offset:-2048
	global_load_dword v154, v[200:201], off
	global_load_dword v155, v[200:201], off offset:2048
	s_mov_b32 s98, 0x199000
	v_lshl_add_u64 v[200:201], v[158:159], 0, s[98:99]
	global_load_dword v156, v[200:201], off offset:-4096
	global_load_dword v157, v[200:201], off offset:-2048
	global_load_dword v160, v[200:201], off
	global_load_dword v161, v[200:201], off offset:2048
	s_mov_b32 s98, 0x19b000
	v_lshl_add_u64 v[200:201], v[158:159], 0, s[98:99]
	global_load_dword v162, v[200:201], off offset:-4096
	global_load_dword v163, v[200:201], off offset:-2048
	global_load_dword v164, v[200:201], off
	global_load_dword v165, v[200:201], off offset:2048
	s_mov_b32 s98, 0x19d000
	v_lshl_add_u64 v[200:201], v[158:159], 0, s[98:99]
	global_load_dword v166, v[200:201], off offset:-4096
	global_load_dword v167, v[200:201], off offset:-2048
	global_load_dword v168, v[200:201], off
	global_load_dword v169, v[200:201], off offset:2048
	s_mov_b32 s98, 0x19f000
	v_lshl_add_u64 v[200:201], v[158:159], 0, s[98:99]
	global_load_dword v170, v[200:201], off offset:-4096
	global_load_dword v171, v[200:201], off offset:-2048
	global_load_dword v172, v[200:201], off
	global_load_dword v173, v[200:201], off offset:2048
.LBB0_543:
	ds_read_b64 v[174:175], v253 offset:0
	ds_read_b64 v[176:177], v253 offset:8
	ds_read_b64 v[180:181], v253 offset:16
	ds_read_b64 v[182:183], v253 offset:24
	ds_read_b64 v[184:185], v253 offset:32
	ds_read_b64 v[186:187], v253 offset:40
	ds_read_b64 v[188:189], v253 offset:48
	ds_read_b64 v[190:191], v253 offset:56
	ds_read_b64 v[192:193], v253 offset:64
	ds_read_b64 v[194:195], v253 offset:72
	ds_read_b64 v[196:197], v253 offset:80
	ds_read_b64 v[198:199], v253 offset:88
	s_waitcnt vmcnt(60) lgkmcnt(8)
	v_pk_fma_f32 v[50:51], v[32:33], v[174:175], v[50:51] op_sel_hi:[0,1,1]
	v_pk_fma_f32 v[26:27], v[32:33], v[174:175], v[26:27] op_sel:[1,0,0] op_sel_hi:[1,1,1]
	v_pk_fma_f32 v[22:23], v[42:43], v[174:175], v[22:23] op_sel_hi:[0,1,1]
	v_pk_fma_f32 v[20:21], v[42:43], v[174:175], v[20:21] op_sel:[1,0,0] op_sel_hi:[1,1,1]
	v_pk_fma_f32 v[38:39], v[32:33], v[176:177], v[38:39] op_sel_hi:[0,1,1]
	v_pk_fma_f32 v[30:31], v[32:33], v[176:177], v[30:31] op_sel:[1,0,0] op_sel_hi:[1,1,1]
	v_pk_fma_f32 v[28:29], v[42:43], v[176:177], v[28:29] op_sel_hi:[0,1,1]
	v_pk_fma_f32 v[24:25], v[42:43], v[176:177], v[24:25] op_sel:[1,0,0] op_sel_hi:[1,1,1]
	v_pk_fma_f32 v[48:49], v[32:33], v[180:181], v[48:49] op_sel_hi:[0,1,1]
	v_pk_fma_f32 v[46:47], v[32:33], v[180:181], v[46:47] op_sel:[1,0,0] op_sel_hi:[1,1,1]
	v_pk_fma_f32 v[44:45], v[42:43], v[180:181], v[44:45] op_sel_hi:[0,1,1]
	v_pk_fma_f32 v[40:41], v[42:43], v[180:181], v[40:41] op_sel:[1,0,0] op_sel_hi:[1,1,1]
	v_pk_fma_f32 v[18:19], v[32:33], v[182:183], v[18:19] op_sel_hi:[0,1,1]
	v_pk_fma_f32 v[16:17], v[32:33], v[182:183], v[16:17] op_sel:[1,0,0] op_sel_hi:[1,1,1]
	v_pk_fma_f32 v[14:15], v[42:43], v[182:183], v[14:15] op_sel_hi:[0,1,1]
	v_pk_fma_f32 v[12:13], v[42:43], v[182:183], v[12:13] op_sel:[1,0,0] op_sel_hi:[1,1,1]
	ds_read_b64 v[174:175], v253 offset:96
	ds_read_b64 v[176:177], v253 offset:104
	ds_read_b64 v[180:181], v253 offset:112
	ds_read_b64 v[182:183], v253 offset:120
	s_waitcnt vmcnt(56) lgkmcnt(8)
	v_pk_fma_f32 v[50:51], v[52:53], v[184:185], v[50:51] op_sel_hi:[0,1,1]
	v_pk_fma_f32 v[26:27], v[52:53], v[184:185], v[26:27] op_sel:[1,0,0] op_sel_hi:[1,1,1]
	v_pk_fma_f32 v[22:23], v[54:55], v[184:185], v[22:23] op_sel_hi:[0,1,1]
	v_pk_fma_f32 v[20:21], v[54:55], v[184:185], v[20:21] op_sel:[1,0,0] op_sel_hi:[1,1,1]
	v_pk_fma_f32 v[38:39], v[52:53], v[186:187], v[38:39] op_sel_hi:[0,1,1]
	v_pk_fma_f32 v[30:31], v[52:53], v[186:187], v[30:31] op_sel:[1,0,0] op_sel_hi:[1,1,1]
	v_pk_fma_f32 v[28:29], v[54:55], v[186:187], v[28:29] op_sel_hi:[0,1,1]
	v_pk_fma_f32 v[24:25], v[54:55], v[186:187], v[24:25] op_sel:[1,0,0] op_sel_hi:[1,1,1]
	v_pk_fma_f32 v[48:49], v[52:53], v[188:189], v[48:49] op_sel_hi:[0,1,1]
	v_pk_fma_f32 v[46:47], v[52:53], v[188:189], v[46:47] op_sel:[1,0,0] op_sel_hi:[1,1,1]
	v_pk_fma_f32 v[44:45], v[54:55], v[188:189], v[44:45] op_sel_hi:[0,1,1]
	v_pk_fma_f32 v[40:41], v[54:55], v[188:189], v[40:41] op_sel:[1,0,0] op_sel_hi:[1,1,1]
	v_pk_fma_f32 v[18:19], v[52:53], v[190:191], v[18:19] op_sel_hi:[0,1,1]
	v_pk_fma_f32 v[16:17], v[52:53], v[190:191], v[16:17] op_sel:[1,0,0] op_sel_hi:[1,1,1]
	v_pk_fma_f32 v[14:15], v[54:55], v[190:191], v[14:15] op_sel_hi:[0,1,1]
	v_pk_fma_f32 v[12:13], v[54:55], v[190:191], v[12:13] op_sel:[1,0,0] op_sel_hi:[1,1,1]
	ds_read_b64 v[184:185], v253 offset:128
	ds_read_b64 v[186:187], v253 offset:136
	ds_read_b64 v[188:189], v253 offset:144
	ds_read_b64 v[190:191], v253 offset:152
	s_waitcnt vmcnt(52) lgkmcnt(8)
	v_pk_fma_f32 v[50:51], v[58:59], v[192:193], v[50:51] op_sel_hi:[0,1,1]
	v_pk_fma_f32 v[26:27], v[58:59], v[192:193], v[26:27] op_sel:[1,0,0] op_sel_hi:[1,1,1]
	v_pk_fma_f32 v[22:23], v[62:63], v[192:193], v[22:23] op_sel_hi:[0,1,1]
	v_pk_fma_f32 v[20:21], v[62:63], v[192:193], v[20:21] op_sel:[1,0,0] op_sel_hi:[1,1,1]
	v_pk_fma_f32 v[38:39], v[58:59], v[194:195], v[38:39] op_sel_hi:[0,1,1]
	v_pk_fma_f32 v[30:31], v[58:59], v[194:195], v[30:31] op_sel:[1,0,0] op_sel_hi:[1,1,1]
	v_pk_fma_f32 v[28:29], v[62:63], v[194:195], v[28:29] op_sel_hi:[0,1,1]
	v_pk_fma_f32 v[24:25], v[62:63], v[194:195], v[24:25] op_sel:[1,0,0] op_sel_hi:[1,1,1]
	v_pk_fma_f32 v[48:49], v[58:59], v[196:197], v[48:49] op_sel_hi:[0,1,1]
	v_pk_fma_f32 v[46:47], v[58:59], v[196:197], v[46:47] op_sel:[1,0,0] op_sel_hi:[1,1,1]
	v_pk_fma_f32 v[44:45], v[62:63], v[196:197], v[44:45] op_sel_hi:[0,1,1]
	v_pk_fma_f32 v[40:41], v[62:63], v[196:197], v[40:41] op_sel:[1,0,0] op_sel_hi:[1,1,1]
	v_pk_fma_f32 v[18:19], v[58:59], v[198:199], v[18:19] op_sel_hi:[0,1,1]
	v_pk_fma_f32 v[16:17], v[58:59], v[198:199], v[16:17] op_sel:[1,0,0] op_sel_hi:[1,1,1]
	v_pk_fma_f32 v[14:15], v[62:63], v[198:199], v[14:15] op_sel_hi:[0,1,1]
	v_pk_fma_f32 v[12:13], v[62:63], v[198:199], v[12:13] op_sel:[1,0,0] op_sel_hi:[1,1,1]
	ds_read_b64 v[192:193], v253 offset:160
	ds_read_b64 v[194:195], v253 offset:168
	ds_read_b64 v[196:197], v253 offset:176
	ds_read_b64 v[198:199], v253 offset:184
	s_waitcnt vmcnt(48) lgkmcnt(8)
	v_pk_fma_f32 v[50:51], v[64:65], v[174:175], v[50:51] op_sel_hi:[0,1,1]
	v_pk_fma_f32 v[26:27], v[64:65], v[174:175], v[26:27] op_sel:[1,0,0] op_sel_hi:[1,1,1]
	v_pk_fma_f32 v[22:23], v[68:69], v[174:175], v[22:23] op_sel_hi:[0,1,1]
	v_pk_fma_f32 v[20:21], v[68:69], v[174:175], v[20:21] op_sel:[1,0,0] op_sel_hi:[1,1,1]
	v_pk_fma_f32 v[38:39], v[64:65], v[176:177], v[38:39] op_sel_hi:[0,1,1]
	v_pk_fma_f32 v[30:31], v[64:65], v[176:177], v[30:31] op_sel:[1,0,0] op_sel_hi:[1,1,1]
	v_pk_fma_f32 v[28:29], v[68:69], v[176:177], v[28:29] op_sel_hi:[0,1,1]
	v_pk_fma_f32 v[24:25], v[68:69], v[176:177], v[24:25] op_sel:[1,0,0] op_sel_hi:[1,1,1]
	v_pk_fma_f32 v[48:49], v[64:65], v[180:181], v[48:49] op_sel_hi:[0,1,1]
	v_pk_fma_f32 v[46:47], v[64:65], v[180:181], v[46:47] op_sel:[1,0,0] op_sel_hi:[1,1,1]
	v_pk_fma_f32 v[44:45], v[68:69], v[180:181], v[44:45] op_sel_hi:[0,1,1]
	v_pk_fma_f32 v[40:41], v[68:69], v[180:181], v[40:41] op_sel:[1,0,0] op_sel_hi:[1,1,1]
	v_pk_fma_f32 v[18:19], v[64:65], v[182:183], v[18:19] op_sel_hi:[0,1,1]
	v_pk_fma_f32 v[16:17], v[64:65], v[182:183], v[16:17] op_sel:[1,0,0] op_sel_hi:[1,1,1]
	v_pk_fma_f32 v[14:15], v[68:69], v[182:183], v[14:15] op_sel_hi:[0,1,1]
	v_pk_fma_f32 v[12:13], v[68:69], v[182:183], v[12:13] op_sel:[1,0,0] op_sel_hi:[1,1,1]
	ds_read_b64 v[174:175], v253 offset:192
	ds_read_b64 v[176:177], v253 offset:200
	ds_read_b64 v[180:181], v253 offset:208
	ds_read_b64 v[182:183], v253 offset:216
	s_waitcnt vmcnt(44) lgkmcnt(8)
	v_pk_fma_f32 v[50:51], v[70:71], v[184:185], v[50:51] op_sel_hi:[0,1,1]
	v_pk_fma_f32 v[26:27], v[70:71], v[184:185], v[26:27] op_sel:[1,0,0] op_sel_hi:[1,1,1]
	v_pk_fma_f32 v[22:23], v[72:73], v[184:185], v[22:23] op_sel_hi:[0,1,1]
	v_pk_fma_f32 v[20:21], v[72:73], v[184:185], v[20:21] op_sel:[1,0,0] op_sel_hi:[1,1,1]
	v_pk_fma_f32 v[38:39], v[70:71], v[186:187], v[38:39] op_sel_hi:[0,1,1]
	v_pk_fma_f32 v[30:31], v[70:71], v[186:187], v[30:31] op_sel:[1,0,0] op_sel_hi:[1,1,1]
	v_pk_fma_f32 v[28:29], v[72:73], v[186:187], v[28:29] op_sel_hi:[0,1,1]
	v_pk_fma_f32 v[24:25], v[72:73], v[186:187], v[24:25] op_sel:[1,0,0] op_sel_hi:[1,1,1]
	v_pk_fma_f32 v[48:49], v[70:71], v[188:189], v[48:49] op_sel_hi:[0,1,1]
	v_pk_fma_f32 v[46:47], v[70:71], v[188:189], v[46:47] op_sel:[1,0,0] op_sel_hi:[1,1,1]
	v_pk_fma_f32 v[44:45], v[72:73], v[188:189], v[44:45] op_sel_hi:[0,1,1]
	v_pk_fma_f32 v[40:41], v[72:73], v[188:189], v[40:41] op_sel:[1,0,0] op_sel_hi:[1,1,1]
	v_pk_fma_f32 v[18:19], v[70:71], v[190:191], v[18:19] op_sel_hi:[0,1,1]
	v_pk_fma_f32 v[16:17], v[70:71], v[190:191], v[16:17] op_sel:[1,0,0] op_sel_hi:[1,1,1]
	v_pk_fma_f32 v[14:15], v[72:73], v[190:191], v[14:15] op_sel_hi:[0,1,1]
	v_pk_fma_f32 v[12:13], v[72:73], v[190:191], v[12:13] op_sel:[1,0,0] op_sel_hi:[1,1,1]
	ds_read_b64 v[184:185], v253 offset:224
	ds_read_b64 v[186:187], v253 offset:232
	ds_read_b64 v[188:189], v253 offset:240
	ds_read_b64 v[190:191], v253 offset:248
	s_waitcnt vmcnt(40) lgkmcnt(8)
	v_pk_fma_f32 v[50:51], v[74:75], v[192:193], v[50:51] op_sel_hi:[0,1,1]
	v_pk_fma_f32 v[26:27], v[74:75], v[192:193], v[26:27] op_sel:[1,0,0] op_sel_hi:[1,1,1]
	v_pk_fma_f32 v[22:23], v[84:85], v[192:193], v[22:23] op_sel_hi:[0,1,1]
	v_pk_fma_f32 v[20:21], v[84:85], v[192:193], v[20:21] op_sel:[1,0,0] op_sel_hi:[1,1,1]
	v_pk_fma_f32 v[38:39], v[74:75], v[194:195], v[38:39] op_sel_hi:[0,1,1]
	v_pk_fma_f32 v[30:31], v[74:75], v[194:195], v[30:31] op_sel:[1,0,0] op_sel_hi:[1,1,1]
	v_pk_fma_f32 v[28:29], v[84:85], v[194:195], v[28:29] op_sel_hi:[0,1,1]
	v_pk_fma_f32 v[24:25], v[84:85], v[194:195], v[24:25] op_sel:[1,0,0] op_sel_hi:[1,1,1]
	v_pk_fma_f32 v[48:49], v[74:75], v[196:197], v[48:49] op_sel_hi:[0,1,1]
	v_pk_fma_f32 v[46:47], v[74:75], v[196:197], v[46:47] op_sel:[1,0,0] op_sel_hi:[1,1,1]
	v_pk_fma_f32 v[44:45], v[84:85], v[196:197], v[44:45] op_sel_hi:[0,1,1]
	v_pk_fma_f32 v[40:41], v[84:85], v[196:197], v[40:41] op_sel:[1,0,0] op_sel_hi:[1,1,1]
	v_pk_fma_f32 v[18:19], v[74:75], v[198:199], v[18:19] op_sel_hi:[0,1,1]
	v_pk_fma_f32 v[16:17], v[74:75], v[198:199], v[16:17] op_sel:[1,0,0] op_sel_hi:[1,1,1]
	v_pk_fma_f32 v[14:15], v[84:85], v[198:199], v[14:15] op_sel_hi:[0,1,1]
	v_pk_fma_f32 v[12:13], v[84:85], v[198:199], v[12:13] op_sel:[1,0,0] op_sel_hi:[1,1,1]
	ds_read_b64 v[192:193], v253 offset:256
	ds_read_b64 v[194:195], v253 offset:264
	ds_read_b64 v[196:197], v253 offset:272
	ds_read_b64 v[198:199], v253 offset:280
	s_waitcnt vmcnt(36) lgkmcnt(8)
	v_pk_fma_f32 v[50:51], v[94:95], v[174:175], v[50:51] op_sel_hi:[0,1,1]
	v_pk_fma_f32 v[26:27], v[94:95], v[174:175], v[26:27] op_sel:[1,0,0] op_sel_hi:[1,1,1]
	v_pk_fma_f32 v[22:23], v[104:105], v[174:175], v[22:23] op_sel_hi:[0,1,1]
	v_pk_fma_f32 v[20:21], v[104:105], v[174:175], v[20:21] op_sel:[1,0,0] op_sel_hi:[1,1,1]
	v_pk_fma_f32 v[38:39], v[94:95], v[176:177], v[38:39] op_sel_hi:[0,1,1]
	v_pk_fma_f32 v[30:31], v[94:95], v[176:177], v[30:31] op_sel:[1,0,0] op_sel_hi:[1,1,1]
	v_pk_fma_f32 v[28:29], v[104:105], v[176:177], v[28:29] op_sel_hi:[0,1,1]
	v_pk_fma_f32 v[24:25], v[104:105], v[176:177], v[24:25] op_sel:[1,0,0] op_sel_hi:[1,1,1]
	v_pk_fma_f32 v[48:49], v[94:95], v[180:181], v[48:49] op_sel_hi:[0,1,1]
	v_pk_fma_f32 v[46:47], v[94:95], v[180:181], v[46:47] op_sel:[1,0,0] op_sel_hi:[1,1,1]
	v_pk_fma_f32 v[44:45], v[104:105], v[180:181], v[44:45] op_sel_hi:[0,1,1]
	v_pk_fma_f32 v[40:41], v[104:105], v[180:181], v[40:41] op_sel:[1,0,0] op_sel_hi:[1,1,1]
	v_pk_fma_f32 v[18:19], v[94:95], v[182:183], v[18:19] op_sel_hi:[0,1,1]
	v_pk_fma_f32 v[16:17], v[94:95], v[182:183], v[16:17] op_sel:[1,0,0] op_sel_hi:[1,1,1]
	v_pk_fma_f32 v[14:15], v[104:105], v[182:183], v[14:15] op_sel_hi:[0,1,1]
	v_pk_fma_f32 v[12:13], v[104:105], v[182:183], v[12:13] op_sel:[1,0,0] op_sel_hi:[1,1,1]
	ds_read_b64 v[174:175], v253 offset:288
	ds_read_b64 v[176:177], v253 offset:296
	ds_read_b64 v[180:181], v253 offset:304
	ds_read_b64 v[182:183], v253 offset:312
	s_waitcnt vmcnt(32) lgkmcnt(8)
	v_pk_fma_f32 v[50:51], v[112:113], v[184:185], v[50:51] op_sel_hi:[0,1,1]
	v_pk_fma_f32 v[26:27], v[112:113], v[184:185], v[26:27] op_sel:[1,0,0] op_sel_hi:[1,1,1]
	v_pk_fma_f32 v[22:23], v[116:117], v[184:185], v[22:23] op_sel_hi:[0,1,1]
	v_pk_fma_f32 v[20:21], v[116:117], v[184:185], v[20:21] op_sel:[1,0,0] op_sel_hi:[1,1,1]
	v_pk_fma_f32 v[38:39], v[112:113], v[186:187], v[38:39] op_sel_hi:[0,1,1]
	v_pk_fma_f32 v[30:31], v[112:113], v[186:187], v[30:31] op_sel:[1,0,0] op_sel_hi:[1,1,1]
	v_pk_fma_f32 v[28:29], v[116:117], v[186:187], v[28:29] op_sel_hi:[0,1,1]
	v_pk_fma_f32 v[24:25], v[116:117], v[186:187], v[24:25] op_sel:[1,0,0] op_sel_hi:[1,1,1]
	v_pk_fma_f32 v[48:49], v[112:113], v[188:189], v[48:49] op_sel_hi:[0,1,1]
	v_pk_fma_f32 v[46:47], v[112:113], v[188:189], v[46:47] op_sel:[1,0,0] op_sel_hi:[1,1,1]
	v_pk_fma_f32 v[44:45], v[116:117], v[188:189], v[44:45] op_sel_hi:[0,1,1]
	v_pk_fma_f32 v[40:41], v[116:117], v[188:189], v[40:41] op_sel:[1,0,0] op_sel_hi:[1,1,1]
	v_pk_fma_f32 v[18:19], v[112:113], v[190:191], v[18:19] op_sel_hi:[0,1,1]
	v_pk_fma_f32 v[16:17], v[112:113], v[190:191], v[16:17] op_sel:[1,0,0] op_sel_hi:[1,1,1]
	v_pk_fma_f32 v[14:15], v[116:117], v[190:191], v[14:15] op_sel_hi:[0,1,1]
	v_pk_fma_f32 v[12:13], v[116:117], v[190:191], v[12:13] op_sel:[1,0,0] op_sel_hi:[1,1,1]
	s_add_u32 s4, s4, 0x20000
	s_addc_u32 s5, s5, 0
	v_lshl_add_u64 v[158:159], v[10:11], 0, s[4:5]
	s_mov_b32 s98, 0x181000
	v_lshl_add_u64 v[200:201], v[158:159], 0, s[98:99]
	global_load_dword v32, v[200:201], off offset:-4096
	global_load_dword v33, v[200:201], off offset:-2048
	global_load_dword v42, v[200:201], off
	global_load_dword v43, v[200:201], off offset:2048
	s_mov_b32 s98, 0x183000
	v_lshl_add_u64 v[200:201], v[158:159], 0, s[98:99]
	global_load_dword v52, v[200:201], off offset:-4096
	global_load_dword v53, v[200:201], off offset:-2048
	global_load_dword v54, v[200:201], off
	global_load_dword v55, v[200:201], off offset:2048
	s_mov_b32 s98, 0x185000
	v_lshl_add_u64 v[200:201], v[158:159], 0, s[98:99]
	global_load_dword v58, v[200:201], off offset:-4096
	global_load_dword v59, v[200:201], off offset:-2048
	global_load_dword v62, v[200:201], off
	global_load_dword v63, v[200:201], off offset:2048
	s_mov_b32 s98, 0x187000
	v_lshl_add_u64 v[200:201], v[158:159], 0, s[98:99]
	global_load_dword v64, v[200:201], off offset:-4096
	global_load_dword v65, v[200:201], off offset:-2048
	global_load_dword v68, v[200:201], off
	global_load_dword v69, v[200:201], off offset:2048
	s_mov_b32 s98, 0x189000
	v_lshl_add_u64 v[200:201], v[158:159], 0, s[98:99]
	global_load_dword v70, v[200:201], off offset:-4096
	global_load_dword v71, v[200:201], off offset:-2048
	global_load_dword v72, v[200:201], off
	global_load_dword v73, v[200:201], off offset:2048
	s_mov_b32 s98, 0x18b000
	v_lshl_add_u64 v[200:201], v[158:159], 0, s[98:99]
	global_load_dword v74, v[200:201], off offset:-4096
	global_load_dword v75, v[200:201], off offset:-2048
	global_load_dword v84, v[200:201], off
	global_load_dword v85, v[200:201], off offset:2048
	s_mov_b32 s98, 0x18d000
	v_lshl_add_u64 v[200:201], v[158:159], 0, s[98:99]
	global_load_dword v94, v[200:201], off offset:-4096
	global_load_dword v95, v[200:201], off offset:-2048
	global_load_dword v104, v[200:201], off
	global_load_dword v105, v[200:201], off offset:2048
	s_mov_b32 s98, 0x18f000
	v_lshl_add_u64 v[200:201], v[158:159], 0, s[98:99]
	global_load_dword v112, v[200:201], off offset:-4096
	global_load_dword v113, v[200:201], off offset:-2048
	global_load_dword v116, v[200:201], off
	global_load_dword v117, v[200:201], off offset:2048
	ds_read_b64 v[184:185], v253 offset:320
	ds_read_b64 v[186:187], v253 offset:328
	ds_read_b64 v[188:189], v253 offset:336
	ds_read_b64 v[190:191], v253 offset:344
	s_waitcnt vmcnt(60) lgkmcnt(8)
	v_pk_fma_f32 v[50:51], v[122:123], v[192:193], v[50:51] op_sel_hi:[0,1,1]
	v_pk_fma_f32 v[26:27], v[122:123], v[192:193], v[26:27] op_sel:[1,0,0] op_sel_hi:[1,1,1]
	v_pk_fma_f32 v[22:23], v[126:127], v[192:193], v[22:23] op_sel_hi:[0,1,1]
	v_pk_fma_f32 v[20:21], v[126:127], v[192:193], v[20:21] op_sel:[1,0,0] op_sel_hi:[1,1,1]
	v_pk_fma_f32 v[38:39], v[122:123], v[194:195], v[38:39] op_sel_hi:[0,1,1]
	v_pk_fma_f32 v[30:31], v[122:123], v[194:195], v[30:31] op_sel:[1,0,0] op_sel_hi:[1,1,1]
	v_pk_fma_f32 v[28:29], v[126:127], v[194:195], v[28:29] op_sel_hi:[0,1,1]
	v_pk_fma_f32 v[24:25], v[126:127], v[194:195], v[24:25] op_sel:[1,0,0] op_sel_hi:[1,1,1]
	v_pk_fma_f32 v[48:49], v[122:123], v[196:197], v[48:49] op_sel_hi:[0,1,1]
	v_pk_fma_f32 v[46:47], v[122:123], v[196:197], v[46:47] op_sel:[1,0,0] op_sel_hi:[1,1,1]
	v_pk_fma_f32 v[44:45], v[126:127], v[196:197], v[44:45] op_sel_hi:[0,1,1]
	v_pk_fma_f32 v[40:41], v[126:127], v[196:197], v[40:41] op_sel:[1,0,0] op_sel_hi:[1,1,1]
	v_pk_fma_f32 v[18:19], v[122:123], v[198:199], v[18:19] op_sel_hi:[0,1,1]
	v_pk_fma_f32 v[16:17], v[122:123], v[198:199], v[16:17] op_sel:[1,0,0] op_sel_hi:[1,1,1]
	v_pk_fma_f32 v[14:15], v[126:127], v[198:199], v[14:15] op_sel_hi:[0,1,1]
	v_pk_fma_f32 v[12:13], v[126:127], v[198:199], v[12:13] op_sel:[1,0,0] op_sel_hi:[1,1,1]
	ds_read_b64 v[192:193], v253 offset:352
	ds_read_b64 v[194:195], v253 offset:360
	ds_read_b64 v[196:197], v253 offset:368
	ds_read_b64 v[198:199], v253 offset:376
	s_waitcnt vmcnt(56) lgkmcnt(8)
	v_pk_fma_f32 v[50:51], v[130:131], v[174:175], v[50:51] op_sel_hi:[0,1,1]
	v_pk_fma_f32 v[26:27], v[130:131], v[174:175], v[26:27] op_sel:[1,0,0] op_sel_hi:[1,1,1]
	v_pk_fma_f32 v[22:23], v[138:139], v[174:175], v[22:23] op_sel_hi:[0,1,1]
	v_pk_fma_f32 v[20:21], v[138:139], v[174:175], v[20:21] op_sel:[1,0,0] op_sel_hi:[1,1,1]
	v_pk_fma_f32 v[38:39], v[130:131], v[176:177], v[38:39] op_sel_hi:[0,1,1]
	v_pk_fma_f32 v[30:31], v[130:131], v[176:177], v[30:31] op_sel:[1,0,0] op_sel_hi:[1,1,1]
	v_pk_fma_f32 v[28:29], v[138:139], v[176:177], v[28:29] op_sel_hi:[0,1,1]
	v_pk_fma_f32 v[24:25], v[138:139], v[176:177], v[24:25] op_sel:[1,0,0] op_sel_hi:[1,1,1]
	v_pk_fma_f32 v[48:49], v[130:131], v[180:181], v[48:49] op_sel_hi:[0,1,1]
	v_pk_fma_f32 v[46:47], v[130:131], v[180:181], v[46:47] op_sel:[1,0,0] op_sel_hi:[1,1,1]
	v_pk_fma_f32 v[44:45], v[138:139], v[180:181], v[44:45] op_sel_hi:[0,1,1]
	v_pk_fma_f32 v[40:41], v[138:139], v[180:181], v[40:41] op_sel:[1,0,0] op_sel_hi:[1,1,1]
	v_pk_fma_f32 v[18:19], v[130:131], v[182:183], v[18:19] op_sel_hi:[0,1,1]
	v_pk_fma_f32 v[16:17], v[130:131], v[182:183], v[16:17] op_sel:[1,0,0] op_sel_hi:[1,1,1]
	v_pk_fma_f32 v[14:15], v[138:139], v[182:183], v[14:15] op_sel_hi:[0,1,1]
	v_pk_fma_f32 v[12:13], v[138:139], v[182:183], v[12:13] op_sel:[1,0,0] op_sel_hi:[1,1,1]
	ds_read_b64 v[174:175], v253 offset:384
	ds_read_b64 v[176:177], v253 offset:392
	ds_read_b64 v[180:181], v253 offset:400
	ds_read_b64 v[182:183], v253 offset:408
	s_waitcnt vmcnt(52) lgkmcnt(8)
	v_pk_fma_f32 v[50:51], v[140:141], v[184:185], v[50:51] op_sel_hi:[0,1,1]
	v_pk_fma_f32 v[26:27], v[140:141], v[184:185], v[26:27] op_sel:[1,0,0] op_sel_hi:[1,1,1]
	v_pk_fma_f32 v[22:23], v[144:145], v[184:185], v[22:23] op_sel_hi:[0,1,1]
	v_pk_fma_f32 v[20:21], v[144:145], v[184:185], v[20:21] op_sel:[1,0,0] op_sel_hi:[1,1,1]
	v_pk_fma_f32 v[38:39], v[140:141], v[186:187], v[38:39] op_sel_hi:[0,1,1]
	v_pk_fma_f32 v[30:31], v[140:141], v[186:187], v[30:31] op_sel:[1,0,0] op_sel_hi:[1,1,1]
	v_pk_fma_f32 v[28:29], v[144:145], v[186:187], v[28:29] op_sel_hi:[0,1,1]
	v_pk_fma_f32 v[24:25], v[144:145], v[186:187], v[24:25] op_sel:[1,0,0] op_sel_hi:[1,1,1]
	v_pk_fma_f32 v[48:49], v[140:141], v[188:189], v[48:49] op_sel_hi:[0,1,1]
	v_pk_fma_f32 v[46:47], v[140:141], v[188:189], v[46:47] op_sel:[1,0,0] op_sel_hi:[1,1,1]
	v_pk_fma_f32 v[44:45], v[144:145], v[188:189], v[44:45] op_sel_hi:[0,1,1]
	v_pk_fma_f32 v[40:41], v[144:145], v[188:189], v[40:41] op_sel:[1,0,0] op_sel_hi:[1,1,1]
	v_pk_fma_f32 v[18:19], v[140:141], v[190:191], v[18:19] op_sel_hi:[0,1,1]
	v_pk_fma_f32 v[16:17], v[140:141], v[190:191], v[16:17] op_sel:[1,0,0] op_sel_hi:[1,1,1]
	v_pk_fma_f32 v[14:15], v[144:145], v[190:191], v[14:15] op_sel_hi:[0,1,1]
	v_pk_fma_f32 v[12:13], v[144:145], v[190:191], v[12:13] op_sel:[1,0,0] op_sel_hi:[1,1,1]
	ds_read_b64 v[184:185], v253 offset:416
	ds_read_b64 v[186:187], v253 offset:424
	ds_read_b64 v[188:189], v253 offset:432
	ds_read_b64 v[190:191], v253 offset:440
	s_waitcnt vmcnt(48) lgkmcnt(8)
	v_pk_fma_f32 v[50:51], v[150:151], v[192:193], v[50:51] op_sel_hi:[0,1,1]
	v_pk_fma_f32 v[26:27], v[150:151], v[192:193], v[26:27] op_sel:[1,0,0] op_sel_hi:[1,1,1]
	v_pk_fma_f32 v[22:23], v[154:155], v[192:193], v[22:23] op_sel_hi:[0,1,1]
	v_pk_fma_f32 v[20:21], v[154:155], v[192:193], v[20:21] op_sel:[1,0,0] op_sel_hi:[1,1,1]
	v_pk_fma_f32 v[38:39], v[150:151], v[194:195], v[38:39] op_sel_hi:[0,1,1]
	v_pk_fma_f32 v[30:31], v[150:151], v[194:195], v[30:31] op_sel:[1,0,0] op_sel_hi:[1,1,1]
	v_pk_fma_f32 v[28:29], v[154:155], v[194:195], v[28:29] op_sel_hi:[0,1,1]
	v_pk_fma_f32 v[24:25], v[154:155], v[194:195], v[24:25] op_sel:[1,0,0] op_sel_hi:[1,1,1]
	v_pk_fma_f32 v[48:49], v[150:151], v[196:197], v[48:49] op_sel_hi:[0,1,1]
	v_pk_fma_f32 v[46:47], v[150:151], v[196:197], v[46:47] op_sel:[1,0,0] op_sel_hi:[1,1,1]
	v_pk_fma_f32 v[44:45], v[154:155], v[196:197], v[44:45] op_sel_hi:[0,1,1]
	v_pk_fma_f32 v[40:41], v[154:155], v[196:197], v[40:41] op_sel:[1,0,0] op_sel_hi:[1,1,1]
	v_pk_fma_f32 v[18:19], v[150:151], v[198:199], v[18:19] op_sel_hi:[0,1,1]
	v_pk_fma_f32 v[16:17], v[150:151], v[198:199], v[16:17] op_sel:[1,0,0] op_sel_hi:[1,1,1]
	v_pk_fma_f32 v[14:15], v[154:155], v[198:199], v[14:15] op_sel_hi:[0,1,1]
	v_pk_fma_f32 v[12:13], v[154:155], v[198:199], v[12:13] op_sel:[1,0,0] op_sel_hi:[1,1,1]
	ds_read_b64 v[192:193], v253 offset:448
	ds_read_b64 v[194:195], v253 offset:456
	ds_read_b64 v[196:197], v253 offset:464
	ds_read_b64 v[198:199], v253 offset:472
	s_waitcnt vmcnt(44) lgkmcnt(8)
	v_pk_fma_f32 v[50:51], v[156:157], v[174:175], v[50:51] op_sel_hi:[0,1,1]
	v_pk_fma_f32 v[26:27], v[156:157], v[174:175], v[26:27] op_sel:[1,0,0] op_sel_hi:[1,1,1]
	v_pk_fma_f32 v[22:23], v[160:161], v[174:175], v[22:23] op_sel_hi:[0,1,1]
	v_pk_fma_f32 v[20:21], v[160:161], v[174:175], v[20:21] op_sel:[1,0,0] op_sel_hi:[1,1,1]
	v_pk_fma_f32 v[38:39], v[156:157], v[176:177], v[38:39] op_sel_hi:[0,1,1]
	v_pk_fma_f32 v[30:31], v[156:157], v[176:177], v[30:31] op_sel:[1,0,0] op_sel_hi:[1,1,1]
	v_pk_fma_f32 v[28:29], v[160:161], v[176:177], v[28:29] op_sel_hi:[0,1,1]
	v_pk_fma_f32 v[24:25], v[160:161], v[176:177], v[24:25] op_sel:[1,0,0] op_sel_hi:[1,1,1]
	v_pk_fma_f32 v[48:49], v[156:157], v[180:181], v[48:49] op_sel_hi:[0,1,1]
	v_pk_fma_f32 v[46:47], v[156:157], v[180:181], v[46:47] op_sel:[1,0,0] op_sel_hi:[1,1,1]
	v_pk_fma_f32 v[44:45], v[160:161], v[180:181], v[44:45] op_sel_hi:[0,1,1]
	v_pk_fma_f32 v[40:41], v[160:161], v[180:181], v[40:41] op_sel:[1,0,0] op_sel_hi:[1,1,1]
	v_pk_fma_f32 v[18:19], v[156:157], v[182:183], v[18:19] op_sel_hi:[0,1,1]
	v_pk_fma_f32 v[16:17], v[156:157], v[182:183], v[16:17] op_sel:[1,0,0] op_sel_hi:[1,1,1]
	v_pk_fma_f32 v[14:15], v[160:161], v[182:183], v[14:15] op_sel_hi:[0,1,1]
	v_pk_fma_f32 v[12:13], v[160:161], v[182:183], v[12:13] op_sel:[1,0,0] op_sel_hi:[1,1,1]
	ds_read_b64 v[174:175], v253 offset:480
	ds_read_b64 v[176:177], v253 offset:488
	ds_read_b64 v[180:181], v253 offset:496
	ds_read_b64 v[182:183], v253 offset:504
	s_waitcnt vmcnt(40) lgkmcnt(8)
	v_pk_fma_f32 v[50:51], v[162:163], v[184:185], v[50:51] op_sel_hi:[0,1,1]
	v_pk_fma_f32 v[26:27], v[162:163], v[184:185], v[26:27] op_sel:[1,0,0] op_sel_hi:[1,1,1]
	v_pk_fma_f32 v[22:23], v[164:165], v[184:185], v[22:23] op_sel_hi:[0,1,1]
	v_pk_fma_f32 v[20:21], v[164:165], v[184:185], v[20:21] op_sel:[1,0,0] op_sel_hi:[1,1,1]
	v_pk_fma_f32 v[38:39], v[162:163], v[186:187], v[38:39] op_sel_hi:[0,1,1]
	v_pk_fma_f32 v[30:31], v[162:163], v[186:187], v[30:31] op_sel:[1,0,0] op_sel_hi:[1,1,1]
	v_pk_fma_f32 v[28:29], v[164:165], v[186:187], v[28:29] op_sel_hi:[0,1,1]
	v_pk_fma_f32 v[24:25], v[164:165], v[186:187], v[24:25] op_sel:[1,0,0] op_sel_hi:[1,1,1]
	v_pk_fma_f32 v[48:49], v[162:163], v[188:189], v[48:49] op_sel_hi:[0,1,1]
	v_pk_fma_f32 v[46:47], v[162:163], v[188:189], v[46:47] op_sel:[1,0,0] op_sel_hi:[1,1,1]
	v_pk_fma_f32 v[44:45], v[164:165], v[188:189], v[44:45] op_sel_hi:[0,1,1]
	v_pk_fma_f32 v[40:41], v[164:165], v[188:189], v[40:41] op_sel:[1,0,0] op_sel_hi:[1,1,1]
	v_pk_fma_f32 v[18:19], v[162:163], v[190:191], v[18:19] op_sel_hi:[0,1,1]
	v_pk_fma_f32 v[16:17], v[162:163], v[190:191], v[16:17] op_sel:[1,0,0] op_sel_hi:[1,1,1]
	v_pk_fma_f32 v[14:15], v[164:165], v[190:191], v[14:15] op_sel_hi:[0,1,1]
	v_pk_fma_f32 v[12:13], v[164:165], v[190:191], v[12:13] op_sel:[1,0,0] op_sel_hi:[1,1,1]
	s_waitcnt vmcnt(36) lgkmcnt(4)
	v_pk_fma_f32 v[50:51], v[166:167], v[192:193], v[50:51] op_sel_hi:[0,1,1]
	v_pk_fma_f32 v[26:27], v[166:167], v[192:193], v[26:27] op_sel:[1,0,0] op_sel_hi:[1,1,1]
	v_pk_fma_f32 v[22:23], v[168:169], v[192:193], v[22:23] op_sel_hi:[0,1,1]
	v_pk_fma_f32 v[20:21], v[168:169], v[192:193], v[20:21] op_sel:[1,0,0] op_sel_hi:[1,1,1]
	v_pk_fma_f32 v[38:39], v[166:167], v[194:195], v[38:39] op_sel_hi:[0,1,1]
	v_pk_fma_f32 v[30:31], v[166:167], v[194:195], v[30:31] op_sel:[1,0,0] op_sel_hi:[1,1,1]
	v_pk_fma_f32 v[28:29], v[168:169], v[194:195], v[28:29] op_sel_hi:[0,1,1]
	v_pk_fma_f32 v[24:25], v[168:169], v[194:195], v[24:25] op_sel:[1,0,0] op_sel_hi:[1,1,1]
	v_pk_fma_f32 v[48:49], v[166:167], v[196:197], v[48:49] op_sel_hi:[0,1,1]
	v_pk_fma_f32 v[46:47], v[166:167], v[196:197], v[46:47] op_sel:[1,0,0] op_sel_hi:[1,1,1]
	v_pk_fma_f32 v[44:45], v[168:169], v[196:197], v[44:45] op_sel_hi:[0,1,1]
	v_pk_fma_f32 v[40:41], v[168:169], v[196:197], v[40:41] op_sel:[1,0,0] op_sel_hi:[1,1,1]
	v_pk_fma_f32 v[18:19], v[166:167], v[198:199], v[18:19] op_sel_hi:[0,1,1]
	v_pk_fma_f32 v[16:17], v[166:167], v[198:199], v[16:17] op_sel:[1,0,0] op_sel_hi:[1,1,1]
	v_pk_fma_f32 v[14:15], v[168:169], v[198:199], v[14:15] op_sel_hi:[0,1,1]
	v_pk_fma_f32 v[12:13], v[168:169], v[198:199], v[12:13] op_sel:[1,0,0] op_sel_hi:[1,1,1]
	s_waitcnt vmcnt(32) lgkmcnt(0)
	v_pk_fma_f32 v[50:51], v[170:171], v[174:175], v[50:51] op_sel_hi:[0,1,1]
	v_pk_fma_f32 v[26:27], v[170:171], v[174:175], v[26:27] op_sel:[1,0,0] op_sel_hi:[1,1,1]
	v_pk_fma_f32 v[22:23], v[172:173], v[174:175], v[22:23] op_sel_hi:[0,1,1]
	v_pk_fma_f32 v[20:21], v[172:173], v[174:175], v[20:21] op_sel:[1,0,0] op_sel_hi:[1,1,1]
	v_pk_fma_f32 v[38:39], v[170:171], v[176:177], v[38:39] op_sel_hi:[0,1,1]
	v_pk_fma_f32 v[30:31], v[170:171], v[176:177], v[30:31] op_sel:[1,0,0] op_sel_hi:[1,1,1]
	v_pk_fma_f32 v[28:29], v[172:173], v[176:177], v[28:29] op_sel_hi:[0,1,1]
	v_pk_fma_f32 v[24:25], v[172:173], v[176:177], v[24:25] op_sel:[1,0,0] op_sel_hi:[1,1,1]
	v_pk_fma_f32 v[48:49], v[170:171], v[180:181], v[48:49] op_sel_hi:[0,1,1]
	v_pk_fma_f32 v[46:47], v[170:171], v[180:181], v[46:47] op_sel:[1,0,0] op_sel_hi:[1,1,1]
	v_pk_fma_f32 v[44:45], v[172:173], v[180:181], v[44:45] op_sel_hi:[0,1,1]
	v_pk_fma_f32 v[40:41], v[172:173], v[180:181], v[40:41] op_sel:[1,0,0] op_sel_hi:[1,1,1]
	v_pk_fma_f32 v[18:19], v[170:171], v[182:183], v[18:19] op_sel_hi:[0,1,1]
	v_pk_fma_f32 v[16:17], v[170:171], v[182:183], v[16:17] op_sel:[1,0,0] op_sel_hi:[1,1,1]
	v_pk_fma_f32 v[14:15], v[172:173], v[182:183], v[14:15] op_sel_hi:[0,1,1]
	v_pk_fma_f32 v[12:13], v[172:173], v[182:183], v[12:13] op_sel:[1,0,0] op_sel_hi:[1,1,1]
	s_mov_b32 s98, 0x191000
	v_lshl_add_u64 v[200:201], v[158:159], 0, s[98:99]
	global_load_dword v122, v[200:201], off offset:-4096
	global_load_dword v123, v[200:201], off offset:-2048
	global_load_dword v126, v[200:201], off
	global_load_dword v127, v[200:201], off offset:2048
	s_mov_b32 s98, 0x193000
	v_lshl_add_u64 v[200:201], v[158:159], 0, s[98:99]
	global_load_dword v130, v[200:201], off offset:-4096
	global_load_dword v131, v[200:201], off offset:-2048
	global_load_dword v138, v[200:201], off
	global_load_dword v139, v[200:201], off offset:2048
	s_mov_b32 s98, 0x195000
	v_lshl_add_u64 v[200:201], v[158:159], 0, s[98:99]
	global_load_dword v140, v[200:201], off offset:-4096
	global_load_dword v141, v[200:201], off offset:-2048
	global_load_dword v144, v[200:201], off
	global_load_dword v145, v[200:201], off offset:2048
	s_mov_b32 s98, 0x197000
	v_lshl_add_u64 v[200:201], v[158:159], 0, s[98:99]
	global_load_dword v150, v[200:201], off offset:-4096
	global_load_dword v151, v[200:201], off offset:-2048
	global_load_dword v154, v[200:201], off
	global_load_dword v155, v[200:201], off offset:2048
	s_mov_b32 s98, 0x199000
	v_lshl_add_u64 v[200:201], v[158:159], 0, s[98:99]
	global_load_dword v156, v[200:201], off offset:-4096
	global_load_dword v157, v[200:201], off offset:-2048
	global_load_dword v160, v[200:201], off
	global_load_dword v161, v[200:201], off offset:2048
	s_mov_b32 s98, 0x19b000
	v_lshl_add_u64 v[200:201], v[158:159], 0, s[98:99]
	global_load_dword v162, v[200:201], off offset:-4096
	global_load_dword v163, v[200:201], off offset:-2048
	global_load_dword v164, v[200:201], off
	global_load_dword v165, v[200:201], off offset:2048
	s_mov_b32 s98, 0x19d000
	v_lshl_add_u64 v[200:201], v[158:159], 0, s[98:99]
	global_load_dword v166, v[200:201], off offset:-4096
	global_load_dword v167, v[200:201], off offset:-2048
	global_load_dword v168, v[200:201], off
	global_load_dword v169, v[200:201], off offset:2048
	s_mov_b32 s98, 0x19f000
	v_lshl_add_u64 v[200:201], v[158:159], 0, s[98:99]
	global_load_dword v170, v[200:201], off offset:-4096
	global_load_dword v171, v[200:201], off offset:-2048
	global_load_dword v172, v[200:201], off
	global_load_dword v173, v[200:201], off offset:2048
	v_add_u32_e32 v253, 0x200, v253
	s_cmp_eq_u32 s4, 0x60000
	s_cbranch_scc0 .LBB0_543
	ds_read_b64 v[174:175], v253 offset:0
	ds_read_b64 v[176:177], v253 offset:8
	ds_read_b64 v[180:181], v253 offset:16
	ds_read_b64 v[182:183], v253 offset:24
	ds_read_b64 v[184:185], v253 offset:32
	ds_read_b64 v[186:187], v253 offset:40
	ds_read_b64 v[188:189], v253 offset:48
	ds_read_b64 v[190:191], v253 offset:56
	ds_read_b64 v[192:193], v253 offset:64
	ds_read_b64 v[194:195], v253 offset:72
	ds_read_b64 v[196:197], v253 offset:80
	ds_read_b64 v[198:199], v253 offset:88
	s_waitcnt vmcnt(60) lgkmcnt(8)
	v_pk_fma_f32 v[50:51], v[32:33], v[174:175], v[50:51] op_sel_hi:[0,1,1]
	v_pk_fma_f32 v[26:27], v[32:33], v[174:175], v[26:27] op_sel:[1,0,0] op_sel_hi:[1,1,1]
	v_pk_fma_f32 v[22:23], v[42:43], v[174:175], v[22:23] op_sel_hi:[0,1,1]
	v_pk_fma_f32 v[20:21], v[42:43], v[174:175], v[20:21] op_sel:[1,0,0] op_sel_hi:[1,1,1]
	v_pk_fma_f32 v[38:39], v[32:33], v[176:177], v[38:39] op_sel_hi:[0,1,1]
	v_pk_fma_f32 v[30:31], v[32:33], v[176:177], v[30:31] op_sel:[1,0,0] op_sel_hi:[1,1,1]
	v_pk_fma_f32 v[28:29], v[42:43], v[176:177], v[28:29] op_sel_hi:[0,1,1]
	v_pk_fma_f32 v[24:25], v[42:43], v[176:177], v[24:25] op_sel:[1,0,0] op_sel_hi:[1,1,1]
	v_pk_fma_f32 v[48:49], v[32:33], v[180:181], v[48:49] op_sel_hi:[0,1,1]
	v_pk_fma_f32 v[46:47], v[32:33], v[180:181], v[46:47] op_sel:[1,0,0] op_sel_hi:[1,1,1]
	v_pk_fma_f32 v[44:45], v[42:43], v[180:181], v[44:45] op_sel_hi:[0,1,1]
	v_pk_fma_f32 v[40:41], v[42:43], v[180:181], v[40:41] op_sel:[1,0,0] op_sel_hi:[1,1,1]
	v_pk_fma_f32 v[18:19], v[32:33], v[182:183], v[18:19] op_sel_hi:[0,1,1]
	v_pk_fma_f32 v[16:17], v[32:33], v[182:183], v[16:17] op_sel:[1,0,0] op_sel_hi:[1,1,1]
	v_pk_fma_f32 v[14:15], v[42:43], v[182:183], v[14:15] op_sel_hi:[0,1,1]
	v_pk_fma_f32 v[12:13], v[42:43], v[182:183], v[12:13] op_sel:[1,0,0] op_sel_hi:[1,1,1]
	ds_read_b64 v[174:175], v253 offset:96
	ds_read_b64 v[176:177], v253 offset:104
	ds_read_b64 v[180:181], v253 offset:112
	ds_read_b64 v[182:183], v253 offset:120
	s_waitcnt vmcnt(56) lgkmcnt(8)
	v_pk_fma_f32 v[50:51], v[52:53], v[184:185], v[50:51] op_sel_hi:[0,1,1]
	v_pk_fma_f32 v[26:27], v[52:53], v[184:185], v[26:27] op_sel:[1,0,0] op_sel_hi:[1,1,1]
	v_pk_fma_f32 v[22:23], v[54:55], v[184:185], v[22:23] op_sel_hi:[0,1,1]
	v_pk_fma_f32 v[20:21], v[54:55], v[184:185], v[20:21] op_sel:[1,0,0] op_sel_hi:[1,1,1]
	v_pk_fma_f32 v[38:39], v[52:53], v[186:187], v[38:39] op_sel_hi:[0,1,1]
	v_pk_fma_f32 v[30:31], v[52:53], v[186:187], v[30:31] op_sel:[1,0,0] op_sel_hi:[1,1,1]
	v_pk_fma_f32 v[28:29], v[54:55], v[186:187], v[28:29] op_sel_hi:[0,1,1]
	v_pk_fma_f32 v[24:25], v[54:55], v[186:187], v[24:25] op_sel:[1,0,0] op_sel_hi:[1,1,1]
	v_pk_fma_f32 v[48:49], v[52:53], v[188:189], v[48:49] op_sel_hi:[0,1,1]
	v_pk_fma_f32 v[46:47], v[52:53], v[188:189], v[46:47] op_sel:[1,0,0] op_sel_hi:[1,1,1]
	v_pk_fma_f32 v[44:45], v[54:55], v[188:189], v[44:45] op_sel_hi:[0,1,1]
	v_pk_fma_f32 v[40:41], v[54:55], v[188:189], v[40:41] op_sel:[1,0,0] op_sel_hi:[1,1,1]
	v_pk_fma_f32 v[18:19], v[52:53], v[190:191], v[18:19] op_sel_hi:[0,1,1]
	v_pk_fma_f32 v[16:17], v[52:53], v[190:191], v[16:17] op_sel:[1,0,0] op_sel_hi:[1,1,1]
	v_pk_fma_f32 v[14:15], v[54:55], v[190:191], v[14:15] op_sel_hi:[0,1,1]
	v_pk_fma_f32 v[12:13], v[54:55], v[190:191], v[12:13] op_sel:[1,0,0] op_sel_hi:[1,1,1]
	ds_read_b64 v[184:185], v253 offset:128
	ds_read_b64 v[186:187], v253 offset:136
	ds_read_b64 v[188:189], v253 offset:144
	ds_read_b64 v[190:191], v253 offset:152
	s_waitcnt vmcnt(52) lgkmcnt(8)
	v_pk_fma_f32 v[50:51], v[58:59], v[192:193], v[50:51] op_sel_hi:[0,1,1]
	v_pk_fma_f32 v[26:27], v[58:59], v[192:193], v[26:27] op_sel:[1,0,0] op_sel_hi:[1,1,1]
	v_pk_fma_f32 v[22:23], v[62:63], v[192:193], v[22:23] op_sel_hi:[0,1,1]
	v_pk_fma_f32 v[20:21], v[62:63], v[192:193], v[20:21] op_sel:[1,0,0] op_sel_hi:[1,1,1]
	v_pk_fma_f32 v[38:39], v[58:59], v[194:195], v[38:39] op_sel_hi:[0,1,1]
	v_pk_fma_f32 v[30:31], v[58:59], v[194:195], v[30:31] op_sel:[1,0,0] op_sel_hi:[1,1,1]
	v_pk_fma_f32 v[28:29], v[62:63], v[194:195], v[28:29] op_sel_hi:[0,1,1]
	v_pk_fma_f32 v[24:25], v[62:63], v[194:195], v[24:25] op_sel:[1,0,0] op_sel_hi:[1,1,1]
	v_pk_fma_f32 v[48:49], v[58:59], v[196:197], v[48:49] op_sel_hi:[0,1,1]
	v_pk_fma_f32 v[46:47], v[58:59], v[196:197], v[46:47] op_sel:[1,0,0] op_sel_hi:[1,1,1]
	v_pk_fma_f32 v[44:45], v[62:63], v[196:197], v[44:45] op_sel_hi:[0,1,1]
	v_pk_fma_f32 v[40:41], v[62:63], v[196:197], v[40:41] op_sel:[1,0,0] op_sel_hi:[1,1,1]
	v_pk_fma_f32 v[18:19], v[58:59], v[198:199], v[18:19] op_sel_hi:[0,1,1]
	v_pk_fma_f32 v[16:17], v[58:59], v[198:199], v[16:17] op_sel:[1,0,0] op_sel_hi:[1,1,1]
	v_pk_fma_f32 v[14:15], v[62:63], v[198:199], v[14:15] op_sel_hi:[0,1,1]
	v_pk_fma_f32 v[12:13], v[62:63], v[198:199], v[12:13] op_sel:[1,0,0] op_sel_hi:[1,1,1]
	ds_read_b64 v[192:193], v253 offset:160
	ds_read_b64 v[194:195], v253 offset:168
	ds_read_b64 v[196:197], v253 offset:176
	ds_read_b64 v[198:199], v253 offset:184
	s_waitcnt vmcnt(48) lgkmcnt(8)
	v_pk_fma_f32 v[50:51], v[64:65], v[174:175], v[50:51] op_sel_hi:[0,1,1]
	v_pk_fma_f32 v[26:27], v[64:65], v[174:175], v[26:27] op_sel:[1,0,0] op_sel_hi:[1,1,1]
	v_pk_fma_f32 v[22:23], v[68:69], v[174:175], v[22:23] op_sel_hi:[0,1,1]
	v_pk_fma_f32 v[20:21], v[68:69], v[174:175], v[20:21] op_sel:[1,0,0] op_sel_hi:[1,1,1]
	v_pk_fma_f32 v[38:39], v[64:65], v[176:177], v[38:39] op_sel_hi:[0,1,1]
	v_pk_fma_f32 v[30:31], v[64:65], v[176:177], v[30:31] op_sel:[1,0,0] op_sel_hi:[1,1,1]
	v_pk_fma_f32 v[28:29], v[68:69], v[176:177], v[28:29] op_sel_hi:[0,1,1]
	v_pk_fma_f32 v[24:25], v[68:69], v[176:177], v[24:25] op_sel:[1,0,0] op_sel_hi:[1,1,1]
	v_pk_fma_f32 v[48:49], v[64:65], v[180:181], v[48:49] op_sel_hi:[0,1,1]
	v_pk_fma_f32 v[46:47], v[64:65], v[180:181], v[46:47] op_sel:[1,0,0] op_sel_hi:[1,1,1]
	v_pk_fma_f32 v[44:45], v[68:69], v[180:181], v[44:45] op_sel_hi:[0,1,1]
	v_pk_fma_f32 v[40:41], v[68:69], v[180:181], v[40:41] op_sel:[1,0,0] op_sel_hi:[1,1,1]
	v_pk_fma_f32 v[18:19], v[64:65], v[182:183], v[18:19] op_sel_hi:[0,1,1]
	v_pk_fma_f32 v[16:17], v[64:65], v[182:183], v[16:17] op_sel:[1,0,0] op_sel_hi:[1,1,1]
	v_pk_fma_f32 v[14:15], v[68:69], v[182:183], v[14:15] op_sel_hi:[0,1,1]
	v_pk_fma_f32 v[12:13], v[68:69], v[182:183], v[12:13] op_sel:[1,0,0] op_sel_hi:[1,1,1]
	ds_read_b64 v[174:175], v253 offset:192
	ds_read_b64 v[176:177], v253 offset:200
	ds_read_b64 v[180:181], v253 offset:208
	ds_read_b64 v[182:183], v253 offset:216
	s_waitcnt vmcnt(44) lgkmcnt(8)
	v_pk_fma_f32 v[50:51], v[70:71], v[184:185], v[50:51] op_sel_hi:[0,1,1]
	v_pk_fma_f32 v[26:27], v[70:71], v[184:185], v[26:27] op_sel:[1,0,0] op_sel_hi:[1,1,1]
	v_pk_fma_f32 v[22:23], v[72:73], v[184:185], v[22:23] op_sel_hi:[0,1,1]
	v_pk_fma_f32 v[20:21], v[72:73], v[184:185], v[20:21] op_sel:[1,0,0] op_sel_hi:[1,1,1]
	v_pk_fma_f32 v[38:39], v[70:71], v[186:187], v[38:39] op_sel_hi:[0,1,1]
	v_pk_fma_f32 v[30:31], v[70:71], v[186:187], v[30:31] op_sel:[1,0,0] op_sel_hi:[1,1,1]
	v_pk_fma_f32 v[28:29], v[72:73], v[186:187], v[28:29] op_sel_hi:[0,1,1]
	v_pk_fma_f32 v[24:25], v[72:73], v[186:187], v[24:25] op_sel:[1,0,0] op_sel_hi:[1,1,1]
	v_pk_fma_f32 v[48:49], v[70:71], v[188:189], v[48:49] op_sel_hi:[0,1,1]
	v_pk_fma_f32 v[46:47], v[70:71], v[188:189], v[46:47] op_sel:[1,0,0] op_sel_hi:[1,1,1]
	v_pk_fma_f32 v[44:45], v[72:73], v[188:189], v[44:45] op_sel_hi:[0,1,1]
	v_pk_fma_f32 v[40:41], v[72:73], v[188:189], v[40:41] op_sel:[1,0,0] op_sel_hi:[1,1,1]
	v_pk_fma_f32 v[18:19], v[70:71], v[190:191], v[18:19] op_sel_hi:[0,1,1]
	v_pk_fma_f32 v[16:17], v[70:71], v[190:191], v[16:17] op_sel:[1,0,0] op_sel_hi:[1,1,1]
	v_pk_fma_f32 v[14:15], v[72:73], v[190:191], v[14:15] op_sel_hi:[0,1,1]
	v_pk_fma_f32 v[12:13], v[72:73], v[190:191], v[12:13] op_sel:[1,0,0] op_sel_hi:[1,1,1]
	ds_read_b64 v[184:185], v253 offset:224
	ds_read_b64 v[186:187], v253 offset:232
	ds_read_b64 v[188:189], v253 offset:240
	ds_read_b64 v[190:191], v253 offset:248
	s_waitcnt vmcnt(40) lgkmcnt(8)
	v_pk_fma_f32 v[50:51], v[74:75], v[192:193], v[50:51] op_sel_hi:[0,1,1]
	v_pk_fma_f32 v[26:27], v[74:75], v[192:193], v[26:27] op_sel:[1,0,0] op_sel_hi:[1,1,1]
	v_pk_fma_f32 v[22:23], v[84:85], v[192:193], v[22:23] op_sel_hi:[0,1,1]
	v_pk_fma_f32 v[20:21], v[84:85], v[192:193], v[20:21] op_sel:[1,0,0] op_sel_hi:[1,1,1]
	v_pk_fma_f32 v[38:39], v[74:75], v[194:195], v[38:39] op_sel_hi:[0,1,1]
	v_pk_fma_f32 v[30:31], v[74:75], v[194:195], v[30:31] op_sel:[1,0,0] op_sel_hi:[1,1,1]
	v_pk_fma_f32 v[28:29], v[84:85], v[194:195], v[28:29] op_sel_hi:[0,1,1]
	v_pk_fma_f32 v[24:25], v[84:85], v[194:195], v[24:25] op_sel:[1,0,0] op_sel_hi:[1,1,1]
	v_pk_fma_f32 v[48:49], v[74:75], v[196:197], v[48:49] op_sel_hi:[0,1,1]
	v_pk_fma_f32 v[46:47], v[74:75], v[196:197], v[46:47] op_sel:[1,0,0] op_sel_hi:[1,1,1]
	v_pk_fma_f32 v[44:45], v[84:85], v[196:197], v[44:45] op_sel_hi:[0,1,1]
	v_pk_fma_f32 v[40:41], v[84:85], v[196:197], v[40:41] op_sel:[1,0,0] op_sel_hi:[1,1,1]
	v_pk_fma_f32 v[18:19], v[74:75], v[198:199], v[18:19] op_sel_hi:[0,1,1]
	v_pk_fma_f32 v[16:17], v[74:75], v[198:199], v[16:17] op_sel:[1,0,0] op_sel_hi:[1,1,1]
	v_pk_fma_f32 v[14:15], v[84:85], v[198:199], v[14:15] op_sel_hi:[0,1,1]
	v_pk_fma_f32 v[12:13], v[84:85], v[198:199], v[12:13] op_sel:[1,0,0] op_sel_hi:[1,1,1]
	ds_read_b64 v[192:193], v253 offset:256
	ds_read_b64 v[194:195], v253 offset:264
	ds_read_b64 v[196:197], v253 offset:272
	ds_read_b64 v[198:199], v253 offset:280
	s_waitcnt vmcnt(36) lgkmcnt(8)
	v_pk_fma_f32 v[50:51], v[94:95], v[174:175], v[50:51] op_sel_hi:[0,1,1]
	v_pk_fma_f32 v[26:27], v[94:95], v[174:175], v[26:27] op_sel:[1,0,0] op_sel_hi:[1,1,1]
	v_pk_fma_f32 v[22:23], v[104:105], v[174:175], v[22:23] op_sel_hi:[0,1,1]
	v_pk_fma_f32 v[20:21], v[104:105], v[174:175], v[20:21] op_sel:[1,0,0] op_sel_hi:[1,1,1]
	v_pk_fma_f32 v[38:39], v[94:95], v[176:177], v[38:39] op_sel_hi:[0,1,1]
	v_pk_fma_f32 v[30:31], v[94:95], v[176:177], v[30:31] op_sel:[1,0,0] op_sel_hi:[1,1,1]
	v_pk_fma_f32 v[28:29], v[104:105], v[176:177], v[28:29] op_sel_hi:[0,1,1]
	v_pk_fma_f32 v[24:25], v[104:105], v[176:177], v[24:25] op_sel:[1,0,0] op_sel_hi:[1,1,1]
	v_pk_fma_f32 v[48:49], v[94:95], v[180:181], v[48:49] op_sel_hi:[0,1,1]
	v_pk_fma_f32 v[46:47], v[94:95], v[180:181], v[46:47] op_sel:[1,0,0] op_sel_hi:[1,1,1]
	v_pk_fma_f32 v[44:45], v[104:105], v[180:181], v[44:45] op_sel_hi:[0,1,1]
	v_pk_fma_f32 v[40:41], v[104:105], v[180:181], v[40:41] op_sel:[1,0,0] op_sel_hi:[1,1,1]
	v_pk_fma_f32 v[18:19], v[94:95], v[182:183], v[18:19] op_sel_hi:[0,1,1]
	v_pk_fma_f32 v[16:17], v[94:95], v[182:183], v[16:17] op_sel:[1,0,0] op_sel_hi:[1,1,1]
	v_pk_fma_f32 v[14:15], v[104:105], v[182:183], v[14:15] op_sel_hi:[0,1,1]
	v_pk_fma_f32 v[12:13], v[104:105], v[182:183], v[12:13] op_sel:[1,0,0] op_sel_hi:[1,1,1]
	ds_read_b64 v[174:175], v253 offset:288
	ds_read_b64 v[176:177], v253 offset:296
	ds_read_b64 v[180:181], v253 offset:304
	ds_read_b64 v[182:183], v253 offset:312
	s_waitcnt vmcnt(32) lgkmcnt(8)
	v_pk_fma_f32 v[50:51], v[112:113], v[184:185], v[50:51] op_sel_hi:[0,1,1]
	v_pk_fma_f32 v[26:27], v[112:113], v[184:185], v[26:27] op_sel:[1,0,0] op_sel_hi:[1,1,1]
	v_pk_fma_f32 v[22:23], v[116:117], v[184:185], v[22:23] op_sel_hi:[0,1,1]
	v_pk_fma_f32 v[20:21], v[116:117], v[184:185], v[20:21] op_sel:[1,0,0] op_sel_hi:[1,1,1]
	v_pk_fma_f32 v[38:39], v[112:113], v[186:187], v[38:39] op_sel_hi:[0,1,1]
	v_pk_fma_f32 v[30:31], v[112:113], v[186:187], v[30:31] op_sel:[1,0,0] op_sel_hi:[1,1,1]
	v_pk_fma_f32 v[28:29], v[116:117], v[186:187], v[28:29] op_sel_hi:[0,1,1]
	v_pk_fma_f32 v[24:25], v[116:117], v[186:187], v[24:25] op_sel:[1,0,0] op_sel_hi:[1,1,1]
	v_pk_fma_f32 v[48:49], v[112:113], v[188:189], v[48:49] op_sel_hi:[0,1,1]
	v_pk_fma_f32 v[46:47], v[112:113], v[188:189], v[46:47] op_sel:[1,0,0] op_sel_hi:[1,1,1]
	v_pk_fma_f32 v[44:45], v[116:117], v[188:189], v[44:45] op_sel_hi:[0,1,1]
	v_pk_fma_f32 v[40:41], v[116:117], v[188:189], v[40:41] op_sel:[1,0,0] op_sel_hi:[1,1,1]
	v_pk_fma_f32 v[18:19], v[112:113], v[190:191], v[18:19] op_sel_hi:[0,1,1]
	v_pk_fma_f32 v[16:17], v[112:113], v[190:191], v[16:17] op_sel:[1,0,0] op_sel_hi:[1,1,1]
	v_pk_fma_f32 v[14:15], v[116:117], v[190:191], v[14:15] op_sel_hi:[0,1,1]
	v_pk_fma_f32 v[12:13], v[116:117], v[190:191], v[12:13] op_sel:[1,0,0] op_sel_hi:[1,1,1]
	ds_read_b64 v[184:185], v253 offset:320
	ds_read_b64 v[186:187], v253 offset:328
	ds_read_b64 v[188:189], v253 offset:336
	ds_read_b64 v[190:191], v253 offset:344
	s_waitcnt vmcnt(28) lgkmcnt(8)
	v_pk_fma_f32 v[50:51], v[122:123], v[192:193], v[50:51] op_sel_hi:[0,1,1]
	v_pk_fma_f32 v[26:27], v[122:123], v[192:193], v[26:27] op_sel:[1,0,0] op_sel_hi:[1,1,1]
	v_pk_fma_f32 v[22:23], v[126:127], v[192:193], v[22:23] op_sel_hi:[0,1,1]
	v_pk_fma_f32 v[20:21], v[126:127], v[192:193], v[20:21] op_sel:[1,0,0] op_sel_hi:[1,1,1]
	v_pk_fma_f32 v[38:39], v[122:123], v[194:195], v[38:39] op_sel_hi:[0,1,1]
	v_pk_fma_f32 v[30:31], v[122:123], v[194:195], v[30:31] op_sel:[1,0,0] op_sel_hi:[1,1,1]
	v_pk_fma_f32 v[28:29], v[126:127], v[194:195], v[28:29] op_sel_hi:[0,1,1]
	v_pk_fma_f32 v[24:25], v[126:127], v[194:195], v[24:25] op_sel:[1,0,0] op_sel_hi:[1,1,1]
	v_pk_fma_f32 v[48:49], v[122:123], v[196:197], v[48:49] op_sel_hi:[0,1,1]
	v_pk_fma_f32 v[46:47], v[122:123], v[196:197], v[46:47] op_sel:[1,0,0] op_sel_hi:[1,1,1]
	v_pk_fma_f32 v[44:45], v[126:127], v[196:197], v[44:45] op_sel_hi:[0,1,1]
	v_pk_fma_f32 v[40:41], v[126:127], v[196:197], v[40:41] op_sel:[1,0,0] op_sel_hi:[1,1,1]
	v_pk_fma_f32 v[18:19], v[122:123], v[198:199], v[18:19] op_sel_hi:[0,1,1]
	v_pk_fma_f32 v[16:17], v[122:123], v[198:199], v[16:17] op_sel:[1,0,0] op_sel_hi:[1,1,1]
	v_pk_fma_f32 v[14:15], v[126:127], v[198:199], v[14:15] op_sel_hi:[0,1,1]
	v_pk_fma_f32 v[12:13], v[126:127], v[198:199], v[12:13] op_sel:[1,0,0] op_sel_hi:[1,1,1]
	ds_read_b64 v[192:193], v253 offset:352
	ds_read_b64 v[194:195], v253 offset:360
	ds_read_b64 v[196:197], v253 offset:368
	ds_read_b64 v[198:199], v253 offset:376
	s_waitcnt vmcnt(24) lgkmcnt(8)
	v_pk_fma_f32 v[50:51], v[130:131], v[174:175], v[50:51] op_sel_hi:[0,1,1]
	v_pk_fma_f32 v[26:27], v[130:131], v[174:175], v[26:27] op_sel:[1,0,0] op_sel_hi:[1,1,1]
	v_pk_fma_f32 v[22:23], v[138:139], v[174:175], v[22:23] op_sel_hi:[0,1,1]
	v_pk_fma_f32 v[20:21], v[138:139], v[174:175], v[20:21] op_sel:[1,0,0] op_sel_hi:[1,1,1]
	v_pk_fma_f32 v[38:39], v[130:131], v[176:177], v[38:39] op_sel_hi:[0,1,1]
	v_pk_fma_f32 v[30:31], v[130:131], v[176:177], v[30:31] op_sel:[1,0,0] op_sel_hi:[1,1,1]
	v_pk_fma_f32 v[28:29], v[138:139], v[176:177], v[28:29] op_sel_hi:[0,1,1]
	v_pk_fma_f32 v[24:25], v[138:139], v[176:177], v[24:25] op_sel:[1,0,0] op_sel_hi:[1,1,1]
	v_pk_fma_f32 v[48:49], v[130:131], v[180:181], v[48:49] op_sel_hi:[0,1,1]
	v_pk_fma_f32 v[46:47], v[130:131], v[180:181], v[46:47] op_sel:[1,0,0] op_sel_hi:[1,1,1]
	v_pk_fma_f32 v[44:45], v[138:139], v[180:181], v[44:45] op_sel_hi:[0,1,1]
	v_pk_fma_f32 v[40:41], v[138:139], v[180:181], v[40:41] op_sel:[1,0,0] op_sel_hi:[1,1,1]
	v_pk_fma_f32 v[18:19], v[130:131], v[182:183], v[18:19] op_sel_hi:[0,1,1]
	v_pk_fma_f32 v[16:17], v[130:131], v[182:183], v[16:17] op_sel:[1,0,0] op_sel_hi:[1,1,1]
	v_pk_fma_f32 v[14:15], v[138:139], v[182:183], v[14:15] op_sel_hi:[0,1,1]
	v_pk_fma_f32 v[12:13], v[138:139], v[182:183], v[12:13] op_sel:[1,0,0] op_sel_hi:[1,1,1]
	ds_read_b64 v[174:175], v253 offset:384
	ds_read_b64 v[176:177], v253 offset:392
	ds_read_b64 v[180:181], v253 offset:400
	ds_read_b64 v[182:183], v253 offset:408
	s_waitcnt vmcnt(20) lgkmcnt(8)
	v_pk_fma_f32 v[50:51], v[140:141], v[184:185], v[50:51] op_sel_hi:[0,1,1]
	v_pk_fma_f32 v[26:27], v[140:141], v[184:185], v[26:27] op_sel:[1,0,0] op_sel_hi:[1,1,1]
	v_pk_fma_f32 v[22:23], v[144:145], v[184:185], v[22:23] op_sel_hi:[0,1,1]
	v_pk_fma_f32 v[20:21], v[144:145], v[184:185], v[20:21] op_sel:[1,0,0] op_sel_hi:[1,1,1]
	v_pk_fma_f32 v[38:39], v[140:141], v[186:187], v[38:39] op_sel_hi:[0,1,1]
	v_pk_fma_f32 v[30:31], v[140:141], v[186:187], v[30:31] op_sel:[1,0,0] op_sel_hi:[1,1,1]
	v_pk_fma_f32 v[28:29], v[144:145], v[186:187], v[28:29] op_sel_hi:[0,1,1]
	v_pk_fma_f32 v[24:25], v[144:145], v[186:187], v[24:25] op_sel:[1,0,0] op_sel_hi:[1,1,1]
	v_pk_fma_f32 v[48:49], v[140:141], v[188:189], v[48:49] op_sel_hi:[0,1,1]
	v_pk_fma_f32 v[46:47], v[140:141], v[188:189], v[46:47] op_sel:[1,0,0] op_sel_hi:[1,1,1]
	v_pk_fma_f32 v[44:45], v[144:145], v[188:189], v[44:45] op_sel_hi:[0,1,1]
	v_pk_fma_f32 v[40:41], v[144:145], v[188:189], v[40:41] op_sel:[1,0,0] op_sel_hi:[1,1,1]
	v_pk_fma_f32 v[18:19], v[140:141], v[190:191], v[18:19] op_sel_hi:[0,1,1]
	v_pk_fma_f32 v[16:17], v[140:141], v[190:191], v[16:17] op_sel:[1,0,0] op_sel_hi:[1,1,1]
	v_pk_fma_f32 v[14:15], v[144:145], v[190:191], v[14:15] op_sel_hi:[0,1,1]
	v_pk_fma_f32 v[12:13], v[144:145], v[190:191], v[12:13] op_sel:[1,0,0] op_sel_hi:[1,1,1]
	ds_read_b64 v[184:185], v253 offset:416
	ds_read_b64 v[186:187], v253 offset:424
	ds_read_b64 v[188:189], v253 offset:432
	ds_read_b64 v[190:191], v253 offset:440
	s_waitcnt vmcnt(16) lgkmcnt(8)
	v_pk_fma_f32 v[50:51], v[150:151], v[192:193], v[50:51] op_sel_hi:[0,1,1]
	v_pk_fma_f32 v[26:27], v[150:151], v[192:193], v[26:27] op_sel:[1,0,0] op_sel_hi:[1,1,1]
	v_pk_fma_f32 v[22:23], v[154:155], v[192:193], v[22:23] op_sel_hi:[0,1,1]
	v_pk_fma_f32 v[20:21], v[154:155], v[192:193], v[20:21] op_sel:[1,0,0] op_sel_hi:[1,1,1]
	v_pk_fma_f32 v[38:39], v[150:151], v[194:195], v[38:39] op_sel_hi:[0,1,1]
	v_pk_fma_f32 v[30:31], v[150:151], v[194:195], v[30:31] op_sel:[1,0,0] op_sel_hi:[1,1,1]
	v_pk_fma_f32 v[28:29], v[154:155], v[194:195], v[28:29] op_sel_hi:[0,1,1]
	v_pk_fma_f32 v[24:25], v[154:155], v[194:195], v[24:25] op_sel:[1,0,0] op_sel_hi:[1,1,1]
	v_pk_fma_f32 v[48:49], v[150:151], v[196:197], v[48:49] op_sel_hi:[0,1,1]
	v_pk_fma_f32 v[46:47], v[150:151], v[196:197], v[46:47] op_sel:[1,0,0] op_sel_hi:[1,1,1]
	v_pk_fma_f32 v[44:45], v[154:155], v[196:197], v[44:45] op_sel_hi:[0,1,1]
	v_pk_fma_f32 v[40:41], v[154:155], v[196:197], v[40:41] op_sel:[1,0,0] op_sel_hi:[1,1,1]
	v_pk_fma_f32 v[18:19], v[150:151], v[198:199], v[18:19] op_sel_hi:[0,1,1]
	v_pk_fma_f32 v[16:17], v[150:151], v[198:199], v[16:17] op_sel:[1,0,0] op_sel_hi:[1,1,1]
	v_pk_fma_f32 v[14:15], v[154:155], v[198:199], v[14:15] op_sel_hi:[0,1,1]
	v_pk_fma_f32 v[12:13], v[154:155], v[198:199], v[12:13] op_sel:[1,0,0] op_sel_hi:[1,1,1]
	ds_read_b64 v[192:193], v253 offset:448
	ds_read_b64 v[194:195], v253 offset:456
	ds_read_b64 v[196:197], v253 offset:464
	ds_read_b64 v[198:199], v253 offset:472
	s_waitcnt vmcnt(12) lgkmcnt(8)
	v_pk_fma_f32 v[50:51], v[156:157], v[174:175], v[50:51] op_sel_hi:[0,1,1]
	v_pk_fma_f32 v[26:27], v[156:157], v[174:175], v[26:27] op_sel:[1,0,0] op_sel_hi:[1,1,1]
	v_pk_fma_f32 v[22:23], v[160:161], v[174:175], v[22:23] op_sel_hi:[0,1,1]
	v_pk_fma_f32 v[20:21], v[160:161], v[174:175], v[20:21] op_sel:[1,0,0] op_sel_hi:[1,1,1]
	v_pk_fma_f32 v[38:39], v[156:157], v[176:177], v[38:39] op_sel_hi:[0,1,1]
	v_pk_fma_f32 v[30:31], v[156:157], v[176:177], v[30:31] op_sel:[1,0,0] op_sel_hi:[1,1,1]
	v_pk_fma_f32 v[28:29], v[160:161], v[176:177], v[28:29] op_sel_hi:[0,1,1]
	v_pk_fma_f32 v[24:25], v[160:161], v[176:177], v[24:25] op_sel:[1,0,0] op_sel_hi:[1,1,1]
	v_pk_fma_f32 v[48:49], v[156:157], v[180:181], v[48:49] op_sel_hi:[0,1,1]
	v_pk_fma_f32 v[46:47], v[156:157], v[180:181], v[46:47] op_sel:[1,0,0] op_sel_hi:[1,1,1]
	v_pk_fma_f32 v[44:45], v[160:161], v[180:181], v[44:45] op_sel_hi:[0,1,1]
	v_pk_fma_f32 v[40:41], v[160:161], v[180:181], v[40:41] op_sel:[1,0,0] op_sel_hi:[1,1,1]
	v_pk_fma_f32 v[18:19], v[156:157], v[182:183], v[18:19] op_sel_hi:[0,1,1]
	v_pk_fma_f32 v[16:17], v[156:157], v[182:183], v[16:17] op_sel:[1,0,0] op_sel_hi:[1,1,1]
	v_pk_fma_f32 v[14:15], v[160:161], v[182:183], v[14:15] op_sel_hi:[0,1,1]
	v_pk_fma_f32 v[12:13], v[160:161], v[182:183], v[12:13] op_sel:[1,0,0] op_sel_hi:[1,1,1]
	ds_read_b64 v[174:175], v253 offset:480
	ds_read_b64 v[176:177], v253 offset:488
	ds_read_b64 v[180:181], v253 offset:496
	ds_read_b64 v[182:183], v253 offset:504
	s_waitcnt vmcnt(8) lgkmcnt(8)
	v_pk_fma_f32 v[50:51], v[162:163], v[184:185], v[50:51] op_sel_hi:[0,1,1]
	v_pk_fma_f32 v[26:27], v[162:163], v[184:185], v[26:27] op_sel:[1,0,0] op_sel_hi:[1,1,1]
	v_pk_fma_f32 v[22:23], v[164:165], v[184:185], v[22:23] op_sel_hi:[0,1,1]
	v_pk_fma_f32 v[20:21], v[164:165], v[184:185], v[20:21] op_sel:[1,0,0] op_sel_hi:[1,1,1]
	v_pk_fma_f32 v[38:39], v[162:163], v[186:187], v[38:39] op_sel_hi:[0,1,1]
	v_pk_fma_f32 v[30:31], v[162:163], v[186:187], v[30:31] op_sel:[1,0,0] op_sel_hi:[1,1,1]
	v_pk_fma_f32 v[28:29], v[164:165], v[186:187], v[28:29] op_sel_hi:[0,1,1]
	v_pk_fma_f32 v[24:25], v[164:165], v[186:187], v[24:25] op_sel:[1,0,0] op_sel_hi:[1,1,1]
	v_pk_fma_f32 v[48:49], v[162:163], v[188:189], v[48:49] op_sel_hi:[0,1,1]
	v_pk_fma_f32 v[46:47], v[162:163], v[188:189], v[46:47] op_sel:[1,0,0] op_sel_hi:[1,1,1]
	v_pk_fma_f32 v[44:45], v[164:165], v[188:189], v[44:45] op_sel_hi:[0,1,1]
	v_pk_fma_f32 v[40:41], v[164:165], v[188:189], v[40:41] op_sel:[1,0,0] op_sel_hi:[1,1,1]
	v_pk_fma_f32 v[18:19], v[162:163], v[190:191], v[18:19] op_sel_hi:[0,1,1]
	v_pk_fma_f32 v[16:17], v[162:163], v[190:191], v[16:17] op_sel:[1,0,0] op_sel_hi:[1,1,1]
	v_pk_fma_f32 v[14:15], v[164:165], v[190:191], v[14:15] op_sel_hi:[0,1,1]
	v_pk_fma_f32 v[12:13], v[164:165], v[190:191], v[12:13] op_sel:[1,0,0] op_sel_hi:[1,1,1]
	s_waitcnt vmcnt(4) lgkmcnt(4)
	v_pk_fma_f32 v[50:51], v[166:167], v[192:193], v[50:51] op_sel_hi:[0,1,1]
	v_pk_fma_f32 v[26:27], v[166:167], v[192:193], v[26:27] op_sel:[1,0,0] op_sel_hi:[1,1,1]
	v_pk_fma_f32 v[22:23], v[168:169], v[192:193], v[22:23] op_sel_hi:[0,1,1]
	v_pk_fma_f32 v[20:21], v[168:169], v[192:193], v[20:21] op_sel:[1,0,0] op_sel_hi:[1,1,1]
	v_pk_fma_f32 v[38:39], v[166:167], v[194:195], v[38:39] op_sel_hi:[0,1,1]
	v_pk_fma_f32 v[30:31], v[166:167], v[194:195], v[30:31] op_sel:[1,0,0] op_sel_hi:[1,1,1]
	v_pk_fma_f32 v[28:29], v[168:169], v[194:195], v[28:29] op_sel_hi:[0,1,1]
	v_pk_fma_f32 v[24:25], v[168:169], v[194:195], v[24:25] op_sel:[1,0,0] op_sel_hi:[1,1,1]
	v_pk_fma_f32 v[48:49], v[166:167], v[196:197], v[48:49] op_sel_hi:[0,1,1]
	v_pk_fma_f32 v[46:47], v[166:167], v[196:197], v[46:47] op_sel:[1,0,0] op_sel_hi:[1,1,1]
	v_pk_fma_f32 v[44:45], v[168:169], v[196:197], v[44:45] op_sel_hi:[0,1,1]
	v_pk_fma_f32 v[40:41], v[168:169], v[196:197], v[40:41] op_sel:[1,0,0] op_sel_hi:[1,1,1]
	v_pk_fma_f32 v[18:19], v[166:167], v[198:199], v[18:19] op_sel_hi:[0,1,1]
	v_pk_fma_f32 v[16:17], v[166:167], v[198:199], v[16:17] op_sel:[1,0,0] op_sel_hi:[1,1,1]
	v_pk_fma_f32 v[14:15], v[168:169], v[198:199], v[14:15] op_sel_hi:[0,1,1]
	v_pk_fma_f32 v[12:13], v[168:169], v[198:199], v[12:13] op_sel:[1,0,0] op_sel_hi:[1,1,1]
	s_waitcnt vmcnt(0) lgkmcnt(0)
	v_pk_fma_f32 v[50:51], v[170:171], v[174:175], v[50:51] op_sel_hi:[0,1,1]
	v_pk_fma_f32 v[26:27], v[170:171], v[174:175], v[26:27] op_sel:[1,0,0] op_sel_hi:[1,1,1]
	v_pk_fma_f32 v[22:23], v[172:173], v[174:175], v[22:23] op_sel_hi:[0,1,1]
	v_pk_fma_f32 v[20:21], v[172:173], v[174:175], v[20:21] op_sel:[1,0,0] op_sel_hi:[1,1,1]
	v_pk_fma_f32 v[38:39], v[170:171], v[176:177], v[38:39] op_sel_hi:[0,1,1]
	v_pk_fma_f32 v[30:31], v[170:171], v[176:177], v[30:31] op_sel:[1,0,0] op_sel_hi:[1,1,1]
	v_pk_fma_f32 v[28:29], v[172:173], v[176:177], v[28:29] op_sel_hi:[0,1,1]
	v_pk_fma_f32 v[24:25], v[172:173], v[176:177], v[24:25] op_sel:[1,0,0] op_sel_hi:[1,1,1]
	v_pk_fma_f32 v[48:49], v[170:171], v[180:181], v[48:49] op_sel_hi:[0,1,1]
	v_pk_fma_f32 v[46:47], v[170:171], v[180:181], v[46:47] op_sel:[1,0,0] op_sel_hi:[1,1,1]
	v_pk_fma_f32 v[44:45], v[172:173], v[180:181], v[44:45] op_sel_hi:[0,1,1]
	v_pk_fma_f32 v[40:41], v[172:173], v[180:181], v[40:41] op_sel:[1,0,0] op_sel_hi:[1,1,1]
	v_pk_fma_f32 v[18:19], v[170:171], v[182:183], v[18:19] op_sel_hi:[0,1,1]
	v_pk_fma_f32 v[16:17], v[170:171], v[182:183], v[16:17] op_sel:[1,0,0] op_sel_hi:[1,1,1]
	v_pk_fma_f32 v[14:15], v[172:173], v[182:183], v[14:15] op_sel_hi:[0,1,1]
	v_pk_fma_f32 v[12:13], v[172:173], v[182:183], v[12:13] op_sel:[1,0,0] op_sel_hi:[1,1,1]
	s_add_u32 s4, s4, 0x20000
	s_addc_u32 s5, s5, 0
	v_cvt_f32_i32_e32 v4, s2
	s_ashr_i32 s5, s2, 31
	s_mov_b32 s4, s2
	s_lshl_b64 s[2:3], s[4:5], 14
	v_mul_f32_e32 v4, 0xc1447cbd, v4
	v_div_scale_f32 v32, s[8:9], s48, s48, v4
	v_rcp_f32_e32 v33, v32
	v_div_scale_f32 v34, vcc, v4, s48, v4
	s_add_u32 s2, s14, s2
	v_fma_f32 v36, -v32, v33, 1.0
	v_fmac_f32_e32 v33, v36, v33
	v_mul_f32_e32 v36, v34, v33
	v_fma_f32 v42, -v32, v36, v34
	v_fmac_f32_e32 v36, v42, v33
	v_fma_f32 v32, -v32, v36, v34
	v_div_fmas_f32 v32, v32, v33, v36
	v_div_fixup_f32 v4, v32, s48, v4
	v_add_f32_e32 v34, 0xc0447cbd, v4
	v_mul_f32_e64 v4, v1, |v34|
	v_mul_f32_e32 v32, 0x3fb8aa3b, v4
	v_fma_f32 v33, v4, s49, -v32
	v_rndne_f32_e32 v36, v32
	v_fmac_f32_e32 v33, 0x32a5705f, v4
	v_sub_f32_e32 v32, v32, v36
	v_add_f32_e32 v32, v32, v33
	v_exp_f32_e32 v32, v32
	v_cvt_i32_f32_e32 v33, v36
	v_cmp_ngt_f32_e32 vcc, s52, v4
	s_addc_u32 s3, s15, s3
	v_ldexp_f32 v32, v32, v33
	v_cndmask_b32_e32 v32, 0, v32, vcc
	v_cmp_nlt_f32_e32 vcc, s53, v4
	v_lshlrev_b32_e32 v4, 1, v0
	s_nop 0
	v_cndmask_b32_e32 v36, v217, v32, vcc
	v_mul_f32_e32 v33, v36, v51
	v_lshlrev_b32_e32 v32, 1, v6
	s_and_saveexec_b64 s[8:9], s[86:87]
	s_xor_b64 s[8:9], exec, s[8:9]
	s_cbranch_execz .LBB0_546
	v_bfe_u32 v43, v33, 16, 1
	v_mul_f32_e32 v42, v36, v50
	v_add3_u32 v33, v33, v43, s54
	global_store_short_d16_hi v32, v33, s[2:3] offset:2048
	v_bfe_u32 v33, v42, 16, 1
	v_add3_u32 v33, v42, v33, s54
	global_store_short_d16_hi v4, v33, s[2:3] offset:4094
